# XCD-aware remap of mLSTM items: workgroups with equal blockIdx%8 get contiguous items (share K/V/C0 tiles per XCD L2), on top of v29
# speedup vs baseline: 1.0114x; 1.0114x over previous
.LBB0_620:
	s_mov_b64 s[56:57], 0x8000
	s_andn2_b64 vcc, exec, s[4:5]
	s_cbranch_vccnz .LBB0_640
	s_and_b32 s5, s33, 7
	s_lshl_b32 s5, s5, 6
	s_bfe_u32 s2, s33, 0x60003
	s_or_b32 s5, s5, s2
	s_and_b32 s2, s33, 0xfffffe00
	s_or_b32 s5, s5, s2
	s_add_i32 s2, s5, 0xfffffa00
	s_lshr_b32 s76, s2, 5
	s_lshl_b32 s4, s76, 10
	s_bfe_u32 s71, s5, 0x20003
	s_bfe_u32 s72, s5, 0x20001
	s_and_b32 s73, s5, 1
	v_mov_b32_e32 v32, v244
	s_add_i32 s38, s4, 0xffffd000
	s_lshl_b32 s39, s76, 8
	s_cmpk_gt_u32 s2, 0x1ff
	v_ashrrev_i32_e32 v39, 2, v32
	s_cselect_b64 s[10:11], -1, 0
	v_and_b32_e32 v0, -16, v39
	v_and_b32_e32 v40, 15, v32
	s_and_b64 s[4:5], s[10:11], exec
	v_lshl_add_u32 v41, s72, 6, v0
	s_cselect_b32 s4, s38, s39
	v_or_b32_e32 v179, v41, v40
	v_add_u32_e32 v146, s4, v179
	v_ashrrev_i32_e32 v147, 31, v146
	v_lshlrev_b64 v[0:1], 11, v[146:147]
	v_bfe_u32 v38, v32, 4, 2
	s_cselect_b32 s74, 31, 7
	s_lshl_b32 s2, s71, 9
	v_lshl_add_u64 v[0:1], s[0:1], 0, v[0:1]
	v_lshl_add_u64 v[0:1], v[0:1], 0, s[2:3]
	v_lshlrev_b32_e32 v34, 4, v38
	v_mov_b32_e32 v35, v96
	v_lshl_add_u64 v[28:29], v[0:1], 0, v[34:35]
	global_load_dwordx4 v[0:3], v[28:29], off
	global_load_dwordx4 v[4:7], v[28:29], off offset:64
	global_load_dwordx4 v[8:11], v[28:29], off offset:128
	global_load_dwordx4 v[12:15], v[28:29], off offset:192
	global_load_dwordx4 v[16:19], v[28:29], off offset:256
	global_load_dwordx4 v[20:23], v[28:29], off offset:320
	global_load_dwordx4 v[24:27], v[28:29], off offset:384
	s_nop 0
	global_load_dwordx4 v[28:31], v[28:29], off offset:448
	s_ashr_i32 s38, s4, 5
	v_ashrrev_i32_e32 v42, 5, v32
	s_movk_i32 s5, 0x210
	s_ashr_i32 s39, s38, 31
	v_lshlrev_b32_e32 v185, 2, v38
	v_mul_lo_u32 v42, v42, s5
	s_movk_i32 s5, 0x60
	v_lshl_or_b32 v186, v38, 5, v248
	v_mul_u32_u24_e32 v38, 0x1b0, v40
	s_lshl_b64 s[42:43], s[38:39], 11
	v_mul_lo_u32 v45, v39, s5
	v_mad_u32_u24 v187, v40, s5, v34
	v_mad_u32_u24 v46, v40, s5, v38
	s_lshl_b32 s5, s73, 8
	s_or_b32 s2, s42, s2
	s_or_b32 s42, s2, s5
	s_lshl_b64 s[42:43], s[42:43], 6
	s_add_u32 s42, s65, s42
	s_addc_u32 s43, s66, s43
	s_lshl_b64 s[38:39], s[38:39], 16
	s_add_u32 s2, s48, s38
	s_addc_u32 s5, s49, s39
	s_lshl_b32 s38, s71, 14
	v_add_u32_e32 v38, s4, v41
	s_add_u32 s38, s2, s38
	v_lshlrev_b32_e32 v36, 3, v32
	v_or_b32_e32 v38, v38, v185
	s_addc_u32 s39, s5, 0
	s_lshl_b32 s2, s76, 3
	v_ashrrev_i32_e32 v37, 31, v36
	v_ashrrev_i32_e32 v39, 31, v38
	s_ashr_i32 s5, s4, 31
	s_lshl_b32 s75, s72, 1
	s_or_b32 s2, s2, 0xffffff80
	v_ashrrev_i32_e32 v33, 31, v32
	v_lshlrev_b64 v[36:37], 1, v[36:37]
	v_lshlrev_b64 v[38:39], 12, v[38:39]
	s_or_b32 s76, s75, 1
	s_or_b32 s77, s62, s2
	s_or_b32 s78, s71, s2
	s_lshl_b64 s[4:5], s[4:5], 2
	v_lshlrev_b32_e32 v43, 4, v32
	v_lshl_add_u32 v184, v32, 2, v248
	v_lshl_add_u64 v[148:149], s[42:43], 0, v[36:37]
	v_lshl_add_u64 v[150:151], s[38:39], 0, v[36:37]
	s_add_u32 s4, s67, s4
	v_lshl_add_u64 v[166:167], v[32:33], 2, s[12:13]
	v_lshl_add_u64 v[168:169], s[16:17], 0, v[36:37]
	v_lshl_add_u64 v[32:33], s[20:21], 0, v[38:39]
	v_lshlrev_b32_e32 v36, 1, v40
	v_mov_b32_e32 v37, v96
	s_addc_u32 s5, s68, s5
	v_lshl_add_u64 v[32:33], v[32:33], 0, v[36:37]
	s_lshl_b32 s2, s71, 10
	v_and_b32_e32 v44, 0x1f0, v43
	v_and_b32_e32 v43, 48, v43
	v_lshl_add_u64 v[32:33], v[32:33], 0, s[2:3]
	s_lshl_b32 s2, s73, 9
	s_waitcnt vmcnt(0)
	s_waitcnt vmcnt(6)
	s_waitcnt vmcnt(5)
	s_waitcnt vmcnt(4)
	s_waitcnt vmcnt(3)
	s_waitcnt vmcnt(2)
	s_waitcnt vmcnt(1)
	s_waitcnt vmcnt(0)
	v_and_b32_e32 v188, 0xffff0000, v10
	v_lshlrev_b32_e32 v189, 16, v11
	v_and_b32_e32 v190, 0xffff0000, v11
	v_lshlrev_b32_e32 v191, 16, v12
	v_and_b32_e32 v192, 0xffff0000, v12
	v_lshlrev_b32_e32 v193, 16, v13
	v_and_b32_e32 v194, 0xffff0000, v13
	v_lshlrev_b32_e32 v195, 16, v14
	v_and_b32_e32 v196, 0xffff0000, v14
	v_lshlrev_b32_e32 v197, 16, v15
	v_and_b32_e32 v198, 0xffff0000, v15
	v_lshlrev_b32_e32 v199, 16, v16
	v_and_b32_e32 v200, 0xffff0000, v16
	v_lshlrev_b32_e32 v201, 16, v17
	v_and_b32_e32 v202, 0xffff0000, v17
	v_lshlrev_b32_e32 v203, 16, v18
	v_and_b32_e32 v204, 0xffff0000, v18
	v_lshlrev_b32_e32 v205, 16, v19
	v_and_b32_e32 v206, 0xffff0000, v19
	v_lshlrev_b32_e32 v207, 16, v20
	v_and_b32_e32 v208, 0xffff0000, v20
	v_lshlrev_b32_e32 v209, 16, v21
	v_and_b32_e32 v210, 0xffff0000, v21
	v_lshlrev_b32_e32 v211, 16, v22
	v_and_b32_e32 v212, 0xffff0000, v22
	v_lshlrev_b32_e32 v213, 16, v23
	v_and_b32_e32 v214, 0xffff0000, v23
	v_lshlrev_b32_e32 v215, 16, v24
	v_and_b32_e32 v216, 0xffff0000, v24
	v_lshlrev_b32_e32 v217, 16, v25
	v_and_b32_e32 v218, 0xffff0000, v25
	v_and_b32_e32 v153, 0xffff0000, v26
	v_lshlrev_b32_e32 v152, 16, v26
	v_and_b32_e32 v155, 0xffff0000, v27
	v_lshlrev_b32_e32 v154, 16, v27
	v_and_b32_e32 v157, 0xffff0000, v28
	v_lshlrev_b32_e32 v156, 16, v28
	v_and_b32_e32 v159, 0xffff0000, v29
	v_lshlrev_b32_e32 v158, 16, v29
	v_and_b32_e32 v161, 0xffff0000, v30
	v_lshlrev_b32_e32 v160, 16, v30
	v_and_b32_e32 v163, 0xffff0000, v31
	v_lshlrev_b32_e32 v162, 16, v31
	v_lshl_add_u64 v[164:165], s[4:5], 0, v[34:35]
	v_lshl_add_u64 v[170:171], v[32:33], 0, s[2:3]
	v_or_b32_e32 v219, 19, v185
	s_mov_b32 s42, 0
	s_mov_b64 s[4:5], -1
	v_add_u32_e32 v220, v46, v34
	v_add_u32_e32 v221, v45, v43
	v_add_u32_e32 v222, v42, v44
	s_barrier
	s_branch .LBB0_623

.LBB0_641:
	s_and_b32 s5, s33, 7
	s_lshl_b32 s5, s5, 6
	s_bfe_u32 s2, s33, 0x60003
	s_or_b32 s5, s5, s2
	s_and_b32 s2, s33, 0xfffffe00
	s_or_b32 s5, s5, s2
	s_ashr_i32 s2, s5, 7
	s_add_i32 s76, s2, 16
	s_lshl_b32 s4, s76, 10
	s_bfe_u32 s71, s5, 0x20005
	s_bfe_u32 s72, s5, 0x40001
	s_and_b32 s73, s5, 1
	v_mov_b32_e32 v32, v244
	s_add_i32 s38, s4, 0xffffd000
	s_lshl_b32 s39, s76, 8
	s_cmp_gt_i32 s2, -1
	v_ashrrev_i32_e32 v39, 2, v32
	s_cselect_b64 s[10:11], -1, 0
	v_and_b32_e32 v0, -16, v39
	v_and_b32_e32 v40, 15, v32
	s_and_b64 s[4:5], s[10:11], exec
	v_lshl_add_u32 v41, s72, 6, v0
	s_cselect_b32 s4, s38, s39
	v_or_b32_e32 v179, v41, v40
	v_add_u32_e32 v146, s4, v179
	v_ashrrev_i32_e32 v147, 31, v146
	v_lshlrev_b64 v[0:1], 11, v[146:147]
	v_bfe_u32 v38, v32, 4, 2
	s_cselect_b32 s74, 31, 7
	s_lshl_b32 s2, s71, 9
	v_lshl_add_u64 v[0:1], s[0:1], 0, v[0:1]
	v_lshl_add_u64 v[0:1], v[0:1], 0, s[2:3]
	v_lshlrev_b32_e32 v34, 4, v38
	v_mov_b32_e32 v35, v96
	v_lshl_add_u64 v[28:29], v[0:1], 0, v[34:35]
	global_load_dwordx4 v[0:3], v[28:29], off
	global_load_dwordx4 v[4:7], v[28:29], off offset:64
	global_load_dwordx4 v[8:11], v[28:29], off offset:128
	global_load_dwordx4 v[12:15], v[28:29], off offset:192
	global_load_dwordx4 v[16:19], v[28:29], off offset:256
	global_load_dwordx4 v[20:23], v[28:29], off offset:320
	global_load_dwordx4 v[24:27], v[28:29], off offset:384
	s_nop 0
	global_load_dwordx4 v[28:31], v[28:29], off offset:448
	s_ashr_i32 s38, s4, 5
	v_ashrrev_i32_e32 v42, 5, v32
	s_movk_i32 s5, 0x210
	s_ashr_i32 s39, s38, 31
	v_lshlrev_b32_e32 v185, 2, v38
	v_mul_lo_u32 v42, v42, s5
	s_movk_i32 s5, 0x60
	v_lshl_or_b32 v186, v38, 5, v248
	v_mul_u32_u24_e32 v38, 0x1b0, v40
	s_lshl_b64 s[42:43], s[38:39], 11
	v_mul_lo_u32 v45, v39, s5
	v_mad_u32_u24 v187, v40, s5, v34
	v_mad_u32_u24 v46, v40, s5, v38
	s_lshl_b32 s5, s73, 8
	s_or_b32 s2, s42, s2
	s_or_b32 s42, s2, s5
	s_lshl_b64 s[42:43], s[42:43], 6
	s_add_u32 s42, s65, s42
	s_addc_u32 s43, s66, s43
	s_lshl_b64 s[38:39], s[38:39], 16
	s_add_u32 s2, s48, s38
	s_addc_u32 s5, s49, s39
	s_lshl_b32 s38, s71, 14
	v_add_u32_e32 v38, s4, v41
	s_add_u32 s38, s2, s38
	v_lshlrev_b32_e32 v36, 3, v32
	v_or_b32_e32 v38, v38, v185
	s_addc_u32 s39, s5, 0
	s_lshl_b32 s2, s76, 3
	v_ashrrev_i32_e32 v37, 31, v36
	v_ashrrev_i32_e32 v39, 31, v38
	s_ashr_i32 s5, s4, 31
	s_lshl_b32 s75, s72, 1
	s_addk_i32 s2, 0xff80
	v_ashrrev_i32_e32 v33, 31, v32
	v_lshlrev_b64 v[36:37], 1, v[36:37]
	v_lshlrev_b64 v[38:39], 12, v[38:39]
	s_or_b32 s76, s75, 1
	s_or_b32 s77, s62, s2
	s_or_b32 s78, s71, s2
	s_lshl_b64 s[4:5], s[4:5], 2
	v_lshlrev_b32_e32 v43, 4, v32
	v_lshl_add_u32 v184, v32, 2, v248
	v_lshl_add_u64 v[148:149], s[42:43], 0, v[36:37]
	v_lshl_add_u64 v[150:151], s[38:39], 0, v[36:37]
	s_add_u32 s4, s67, s4
	v_lshl_add_u64 v[166:167], v[32:33], 2, s[12:13]
	v_lshl_add_u64 v[168:169], s[16:17], 0, v[36:37]
	v_lshl_add_u64 v[32:33], s[20:21], 0, v[38:39]
	v_lshlrev_b32_e32 v36, 1, v40
	v_mov_b32_e32 v37, v96
	s_addc_u32 s5, s68, s5
	v_lshl_add_u64 v[32:33], v[32:33], 0, v[36:37]
	s_lshl_b32 s2, s71, 10
	v_and_b32_e32 v44, 0x1f0, v43
	v_and_b32_e32 v43, 48, v43
	v_lshl_add_u64 v[32:33], v[32:33], 0, s[2:3]
	s_lshl_b32 s2, s73, 9
	s_mov_b64 s[56:57], 0x8000
	s_waitcnt vmcnt(0)
	s_nop 0
	v_and_b32_e32 v188, 0xffff0000, v10
	v_lshlrev_b32_e32 v189, 16, v11
	v_and_b32_e32 v190, 0xffff0000, v11
	v_lshlrev_b32_e32 v191, 16, v12
	v_and_b32_e32 v192, 0xffff0000, v12
	v_lshlrev_b32_e32 v193, 16, v13
	v_and_b32_e32 v194, 0xffff0000, v13
	v_lshlrev_b32_e32 v195, 16, v14
	v_and_b32_e32 v196, 0xffff0000, v14
	v_lshlrev_b32_e32 v197, 16, v15
	v_and_b32_e32 v198, 0xffff0000, v15
	v_lshlrev_b32_e32 v199, 16, v16
	v_and_b32_e32 v200, 0xffff0000, v16
	v_lshlrev_b32_e32 v201, 16, v17
	v_and_b32_e32 v202, 0xffff0000, v17
	v_lshlrev_b32_e32 v203, 16, v18
	v_and_b32_e32 v204, 0xffff0000, v18
	v_lshlrev_b32_e32 v205, 16, v19
	v_and_b32_e32 v206, 0xffff0000, v19
	v_lshlrev_b32_e32 v207, 16, v20
	v_and_b32_e32 v208, 0xffff0000, v20
	v_lshlrev_b32_e32 v209, 16, v21
	v_and_b32_e32 v210, 0xffff0000, v21
	v_lshlrev_b32_e32 v211, 16, v22
	v_and_b32_e32 v212, 0xffff0000, v22
	v_lshlrev_b32_e32 v213, 16, v23
	v_and_b32_e32 v214, 0xffff0000, v23
	v_lshlrev_b32_e32 v215, 16, v24
	v_and_b32_e32 v216, 0xffff0000, v24
	v_lshlrev_b32_e32 v217, 16, v25
	v_and_b32_e32 v218, 0xffff0000, v25
	v_and_b32_e32 v153, 0xffff0000, v26
	v_lshlrev_b32_e32 v152, 16, v26
	v_and_b32_e32 v155, 0xffff0000, v27
	v_lshlrev_b32_e32 v154, 16, v27
	v_and_b32_e32 v157, 0xffff0000, v28
	v_lshlrev_b32_e32 v156, 16, v28
	v_and_b32_e32 v159, 0xffff0000, v29
	v_lshlrev_b32_e32 v158, 16, v29
	v_and_b32_e32 v161, 0xffff0000, v30
	v_lshlrev_b32_e32 v160, 16, v30
	v_and_b32_e32 v163, 0xffff0000, v31
	v_lshlrev_b32_e32 v162, 16, v31
	v_lshl_add_u64 v[164:165], s[4:5], 0, v[34:35]
	v_lshl_add_u64 v[170:171], v[32:33], 0, s[2:3]
	v_or_b32_e32 v219, 19, v185
	s_mov_b32 s42, 0
	s_mov_b64 s[4:5], -1
	v_add_u32_e32 v220, v46, v34
	v_add_u32_e32 v221, v45, v43
	v_add_u32_e32 v222, v42, v44
	s_waitcnt lgkmcnt(0)
	s_barrier
	s_branch .LBB0_643
